# grid barrier: L1 invalidate (buffer_inv sc1) issued right after the arrival atomic instead of after the release, overlapping it with the wait
# speedup vs baseline: 1.0476x; 1.0114x over previous
.LBB0_50:
	s_mov_b64 s[10:11], exec
	v_mbcnt_lo_u32_b32 v1, s10, 0
	v_mbcnt_hi_u32_b32 v1, s11, v1
	v_cmp_eq_u32_e32 vcc, 0, v1
	s_and_saveexec_b64 s[6:7], vcc
	s_cbranch_execz .LBB0_52
	s_lshl_b32 s3, s33, 8
	s_add_u32 s12, s76, s3
	s_addc_u32 s13, s77, 0
	s_bcnt1_i32_b64 s3, s[10:11]
	v_mov_b32_e32 v3, 0x1000
	v_mov_b32_e32 v4, s3
	global_atomic_add v3, v3, v4, s[12:13] offset:1024 sc0
	buffer_inv sc1
.LBB0_52:
	s_or_b64 exec, exec, s[6:7]
	v_cvt_f32_u32_e32 v4, v2
	s_waitcnt vmcnt(1)
	v_readfirstlane_b32 s3, v3
	v_sub_u32_e32 v3, 0, v2
	v_rcp_iflag_f32_e32 v4, v4
	v_add_u32_e32 v5, s3, v1
	v_mul_f32_e32 v4, 0x4f7ffffe, v4
	v_cvt_u32_f32_e32 v4, v4
	v_mul_lo_u32 v1, v3, v4
	v_mul_hi_u32 v1, v4, v1
	v_add_u32_e32 v1, v4, v1
	v_mul_hi_u32 v1, v5, v1
	v_mul_lo_u32 v3, v1, v2
	v_sub_u32_e32 v3, v5, v3
	v_add_u32_e32 v4, 1, v1
	v_cmp_ge_u32_e32 vcc, v3, v2
	s_nop 1
	v_cndmask_b32_e32 v1, v1, v4, vcc
	v_sub_u32_e32 v4, v3, v2
	v_cndmask_b32_e32 v3, v3, v4, vcc
	v_add_u32_e32 v4, 1, v1
	v_cmp_ge_u32_e32 vcc, v3, v2
	v_add_u32_e32 v3, 1, v5
	s_nop 0
	v_cndmask_b32_e32 v1, v1, v4, vcc
	v_mul_lo_u32 v4, v2, v1
	v_add_u32_e32 v2, v4, v2
	v_cmp_ne_u32_e32 vcc, v3, v2
	s_and_saveexec_b64 s[6:7], vcc
	s_xor_b64 s[6:7], exec, s[6:7]
	s_cbranch_execz .LBB0_66
	s_waitcnt lgkmcnt(0)
	v_mov_b32_e32 v0, 0x4000
	global_load_dword v0, v0, s[94:95] offset:1280 sc1
	s_add_u32 s14, s94, 0x4500
	s_addc_u32 s15, s95, 0
	s_waitcnt vmcnt(0)
	v_cmp_eq_u32_e32 vcc, v0, v1
	s_and_saveexec_b64 s[10:11], vcc
	s_cbranch_execz .LBB0_65
	s_add_u32 s12, s94, 0x1200
	s_addc_u32 s13, s95, 0
	s_mov_b32 s3, 1
	s_mov_b64 s[16:17], 0
	v_mov_b32_e32 v0, 0
	s_branch .LBB0_56

.LBB0_65:
	s_or_b64 exec, exec, s[10:11]
	s_waitcnt vmcnt(0)
	s_waitcnt vmcnt(0)

.LBB0_83:
	s_or_b64 exec, exec, s[6:7]
	s_waitcnt vmcnt(0)
	s_waitcnt vmcnt(0)

.LBB0_211:
	s_mov_b64 s[8:9], exec
	v_mbcnt_lo_u32_b32 v1, s8, 0
	v_mbcnt_hi_u32_b32 v1, s9, v1
	v_cmp_eq_u32_e32 vcc, 0, v1
	s_and_saveexec_b64 s[6:7], vcc
	s_cbranch_execz .LBB0_213
	s_lshl_b32 s3, s33, 8
	s_add_u32 s10, s76, s3
	s_addc_u32 s11, s77, 0
	s_bcnt1_i32_b64 s3, s[8:9]
	v_mov_b32_e32 v3, 0x1000
	v_mov_b32_e32 v4, s3
	global_atomic_add v3, v3, v4, s[10:11] offset:1024 sc0
	buffer_inv sc1
.LBB0_213:
	s_or_b64 exec, exec, s[6:7]
	v_cvt_f32_u32_e32 v4, v2
	s_waitcnt vmcnt(1)
	v_readfirstlane_b32 s3, v3
	v_sub_u32_e32 v3, 0, v2
	v_rcp_iflag_f32_e32 v4, v4
	v_add_u32_e32 v5, s3, v1
	v_mul_f32_e32 v4, 0x4f7ffffe, v4
	v_cvt_u32_f32_e32 v4, v4
	v_mul_lo_u32 v1, v3, v4
	v_mul_hi_u32 v1, v4, v1
	v_add_u32_e32 v1, v4, v1
	v_mul_hi_u32 v1, v5, v1
	v_mul_lo_u32 v3, v1, v2
	v_sub_u32_e32 v3, v5, v3
	v_add_u32_e32 v4, 1, v1
	v_cmp_ge_u32_e32 vcc, v3, v2
	s_nop 1
	v_cndmask_b32_e32 v1, v1, v4, vcc
	v_sub_u32_e32 v4, v3, v2
	v_cndmask_b32_e32 v3, v3, v4, vcc
	v_add_u32_e32 v4, 1, v1
	v_cmp_ge_u32_e32 vcc, v3, v2
	v_add_u32_e32 v3, 1, v5
	s_nop 0
	v_cndmask_b32_e32 v1, v1, v4, vcc
	v_mul_lo_u32 v4, v2, v1
	v_add_u32_e32 v2, v4, v2
	v_cmp_ne_u32_e32 vcc, v3, v2
	s_and_saveexec_b64 s[6:7], vcc
	s_xor_b64 s[6:7], exec, s[6:7]
	s_cbranch_execz .LBB0_227
	s_waitcnt lgkmcnt(0)
	v_mov_b32_e32 v0, 0x4000
	global_load_dword v0, v0, s[94:95] offset:1280 sc1
	s_add_u32 s12, s94, 0x4500
	s_addc_u32 s13, s95, 0
	s_waitcnt vmcnt(0)
	v_cmp_eq_u32_e32 vcc, v0, v1
	s_and_saveexec_b64 s[8:9], vcc
	s_cbranch_execz .LBB0_226
	s_add_u32 s10, s94, 0x1200
	s_addc_u32 s11, s95, 0
	s_mov_b32 s3, 1
	s_mov_b64 s[14:15], 0
	v_mov_b32_e32 v0, 0
	s_branch .LBB0_217

.LBB0_226:
	s_or_b64 exec, exec, s[8:9]
	s_waitcnt vmcnt(0)
	s_waitcnt vmcnt(0)

.LBB0_860:
	s_mov_b64 s[6:7], exec
	v_mbcnt_lo_u32_b32 v1, s6, 0
	v_mbcnt_hi_u32_b32 v1, s7, v1
	v_cmp_eq_u32_e32 vcc, 0, v1
	s_and_saveexec_b64 s[4:5], vcc
	s_cbranch_execz .LBB0_862
	s_lshl_b32 s3, s33, 8
	s_add_u32 s8, s76, s3
	s_addc_u32 s9, s77, 0
	s_bcnt1_i32_b64 s3, s[6:7]
	v_mov_b32_e32 v3, 0x1000
	v_mov_b32_e32 v4, s3
	global_atomic_add v3, v3, v4, s[8:9] offset:1024 sc0
	buffer_inv sc1
.LBB0_862:
	s_or_b64 exec, exec, s[4:5]
	v_cvt_f32_u32_e32 v4, v2
	s_waitcnt vmcnt(1)
	v_readfirstlane_b32 s3, v3
	v_sub_u32_e32 v3, 0, v2
	v_rcp_iflag_f32_e32 v4, v4
	v_add_u32_e32 v5, s3, v1
	v_mul_f32_e32 v4, 0x4f7ffffe, v4
	v_cvt_u32_f32_e32 v4, v4
	v_mul_lo_u32 v1, v3, v4
	v_mul_hi_u32 v1, v4, v1
	v_add_u32_e32 v1, v4, v1
	v_mul_hi_u32 v1, v5, v1
	v_mul_lo_u32 v3, v1, v2
	v_sub_u32_e32 v3, v5, v3
	v_add_u32_e32 v4, 1, v1
	v_cmp_ge_u32_e32 vcc, v3, v2
	s_nop 1
	v_cndmask_b32_e32 v1, v1, v4, vcc
	v_sub_u32_e32 v4, v3, v2
	v_cndmask_b32_e32 v3, v3, v4, vcc
	v_add_u32_e32 v4, 1, v1
	v_cmp_ge_u32_e32 vcc, v3, v2
	v_add_u32_e32 v3, 1, v5
	s_nop 0
	v_cndmask_b32_e32 v1, v1, v4, vcc
	v_mul_lo_u32 v4, v2, v1
	v_add_u32_e32 v2, v4, v2
	v_cmp_ne_u32_e32 vcc, v3, v2
	s_and_saveexec_b64 s[4:5], vcc
	s_xor_b64 s[4:5], exec, s[4:5]
	s_cbranch_execz .LBB0_876
	s_waitcnt lgkmcnt(0)
	v_mov_b32_e32 v0, 0x4000
	global_load_dword v0, v0, s[94:95] offset:1280 sc1
	s_add_u32 s10, s94, 0x4500
	s_addc_u32 s11, s95, 0
	s_waitcnt vmcnt(0)
	v_cmp_eq_u32_e32 vcc, v0, v1
	s_and_saveexec_b64 s[6:7], vcc
	s_cbranch_execz .LBB0_875
	s_add_u32 s8, s94, 0x1200
	s_addc_u32 s9, s95, 0
	s_mov_b32 s3, 1
	s_mov_b64 s[12:13], 0
	v_mov_b32_e32 v0, 0
	s_branch .LBB0_866

.LBB0_893:
	s_or_b64 exec, exec, s[4:5]
	s_waitcnt vmcnt(0)
	s_waitcnt vmcnt(0)
